# P4 rewritten by hand: 128-deep K steps (16 MFMA per barrier), fragment reads ahead of MFMAs, two-stage global prefetch
# speedup vs baseline: 1.0215x; 1.0215x over previous
; DI int tid8_op() { int t = threadIdx.x; asm volatile("" : "+v"(t)); return t; }
; DI void phase4(const Params& p, int l, unsigned char* smem) {
;     unsigned char* ws = p.ws; asm volatile("" : "+s"(ws));
;     const int tid = tid8_op(), lane = tid & 63, w = __builtin_amdgcn_readfirstlane(tid >> 6), wr = w >> 2, wc = w & 3, r = lane & 31, h = lane >> 5;
;     const bf16_t* YB = (const bf16_t*)(ws + O_YB); const bf16_t* MR = (const bf16_t*)(ws + O_MR);
;     const bf16_t* WMU = (const bf16_t*)(ws + O_WMU + l * SZ_WMU); const bf16_t* WBR = (const bf16_t*)(ws + O_WBR + l * SZ_WBR);
;     const int G = gridDim.x, ntl = 2048, vb = blockIdx.x;
;     if (vb >= ntl) return;
;     const int nmine = (ntl - vb + G - 1) / G, gmax = nmine * 24 - 1;
;     bf16_t* sA = (bf16_t*)smem; bf16_t* sB = sA + 2 * TILE_E;
;     const int srow = tid >> 3, skc = (tid & 7) * 8;
;     const unsigned o128 = (unsigned)((srow * 128 + skc) * 2), s128 = 128u * 128u, o1024 = (unsigned)((srow * 1024 + skc) * 2), s1024 = 1024u * 128u;
;     auto ISS = [&](Stg4& R, int g) {
;         g = g < gmax ? g : gmax;
;         const int i = g / 24, v = g - i * 24, n = v / 6, jj = v - n * 6;
;         const int t = vb + i * G, xcd = t & 7, j = t >> 3, m0 = (32 * xcd + (j >> 3)) * 128, c0 = (j & 7) * 128;
;         if (jj < 2) stg4_issue(R, MR + (size_t)m0 * 128 + jj * 64, o128, s128, WMU + (size_t)(n * 1024 + c0) * 128 + jj * 64, o128, s128);
;         else stg4_issue(R, YB + (size_t)m0 * 1024 + n * 256 + (jj - 2) * 64, o1024, s1024, WBR + (size_t)c0 * 1024 + n * 256 + (jj - 2) * 64, o1024, s1024);
;     };
;     Stg4 R0, R1;
;     ISS(R0, 0); ISS(R1, 1);
;     stg4_commit(R0, sA, sB, srow, skc);
;     ISS(R0, 2);
.LBB0_850:
	s_or_b64 exec, exec, s[36:37]
	v_readlane_b32 s0, v253, 40
	s_mov_b64 s[4:5], s[76:77]
	v_mov_b32_e32 v22, v214
	v_readlane_b32 s1, v253, 41
	s_waitcnt lgkmcnt(0)
	s_barrier
	s_and_b64 vcc, exec, s[0:1]
	v_readfirstlane_b32 s12, v22
	s_cbranch_vccz .LBB0_892
	s_add_u32 s6, s4, 0x1a4c3900
	s_addc_u32 s7, s5, 0
	s_add_u32 s8, s4, 0x15080000
	s_addc_u32 s9, s5, 0
	v_readlane_b32 s0, v254, 56
	v_readlane_b32 s1, v254, 57
	s_add_u32 s10, s4, s0
	s_addc_u32 s11, s5, s1
	s_add_u32 s10, s10, 0x2480000
	s_addc_u32 s11, s11, 0
	s_lshl_b64 s[12:13], s[40:41], 21
	s_add_u32 s12, s4, s12
	s_addc_u32 s13, s5, s13
	s_add_u32 s12, s12, 0x2880000
	s_addc_u32 s13, s13, 0
	s_add_u32 s14, s4, 0x3880000
	s_addc_u32 s15, s5, 0
	v_and_b32_e32 v0, 31, v214
	v_bfe_u32 v2, v214, 5, 1
	v_readfirstlane_b32 s0, v214
	s_lshr_b32 s0, s0, 6
	s_lshr_b32 s1, s0, 2
	s_and_b32 s0, s0, 3
	v_lshlrev_b32_e32 v186, 4, v214
	v_add_u32_e32 v187, 0x2000, v186
	v_add_u32_e32 v188, 0x4000, v186
	v_add_u32_e32 v189, 0x6000, v186
	v_lshrrev_b32_e32 v3, 4, v214
	v_and_b32_e32 v4, 15, v214
	v_lshlrev_b32_e32 v5, 4, v4
	v_lshl_add_u32 v190, v3, 11, v5
	v_add_u32_e32 v191, 0x10000, v190
	v_add_u32_e32 v192, 0x20000, v190
	v_add_u32_e32 v193, 0x30000, v190
	v_mul_u32_u24_e32 v194, 0x110, v3
	v_add_u32_e32 v194, v194, v5
	v_add_u32_e32 v195, 0x11000, v194
	s_lshl_b32 s16, s1, 6
	v_add_u32_e32 v3, s16, v0
	v_mul_u32_u24_e32 v3, 0x110, v3
	v_lshl_add_u32 v196, v2, 4, v3
	v_add_u32_e32 v197, 0x11000, v196
	s_lshl_b32 s16, s0, 5
	v_add_u32_e32 v3, s16, v0
	v_mul_u32_u24_e32 v3, 0x110, v3
	v_lshl_add_u32 v3, v2, 4, v3
	v_add_u32_e32 v198, 0x8800, v3
	v_add_u32_e32 v199, 0x11000, v198
	v_lshlrev_b32_e32 v3, 2, v2
	s_lshl_b32 s16, s1, 6
	v_add_u32_e32 v3, s16, v3
	v_lshlrev_b32_e32 v3, 11, v3
	s_lshl_b32 s16, s0, 5
	v_add_u32_e32 v4, s16, v0
	v_lshl_add_u32 v200, v4, 1, v3
	v_mov_b32_e32 v66, 0
	v_mov_b32_e32 v67, 0
	v_mov_b32_e32 v68, 0
	v_mov_b32_e32 v69, 0
	v_mov_b32_e32 v70, 0
	v_mov_b32_e32 v71, 0
	v_mov_b32_e32 v72, 0
	v_mov_b32_e32 v73, 0
	v_mov_b32_e32 v74, 0
	v_mov_b32_e32 v75, 0
	v_mov_b32_e32 v76, 0
	v_mov_b32_e32 v77, 0
	v_mov_b32_e32 v78, 0
	v_mov_b32_e32 v79, 0
	v_mov_b32_e32 v80, 0
	v_mov_b32_e32 v81, 0
	v_mov_b32_e32 v82, 0
	v_mov_b32_e32 v83, 0
	v_mov_b32_e32 v84, 0
	v_mov_b32_e32 v85, 0
	v_mov_b32_e32 v86, 0
	v_mov_b32_e32 v87, 0
	v_mov_b32_e32 v88, 0
	v_mov_b32_e32 v89, 0
	v_mov_b32_e32 v90, 0
	v_mov_b32_e32 v91, 0
	v_mov_b32_e32 v92, 0
	v_mov_b32_e32 v93, 0
	v_mov_b32_e32 v94, 0
	v_mov_b32_e32 v95, 0
	v_mov_b32_e32 v96, 0
	v_mov_b32_e32 v97, 0
	s_mov_b32 s25, s2
	s_mov_b32 s24, 0
	s_and_b32 s20, s25, 7
	s_lshl_b32 s20, s20, 5
	s_lshr_b32 s21, s25, 6
	s_add_i32 s20, s20, s21
	s_lshl_b32 s26, s20, 7
	s_bfe_u32 s20, s25, 0x30003
	s_lshl_b32 s27, s20, 7
	s_mov_b32 s28, 0
	s_lshl_b32 s20, s26, 8
	s_add_u32 s16, s8, s20
	s_addc_u32 s17, s9, 0
	s_lshl_b32 s20, s28, 10
	s_add_i32 s20, s20, s27
	s_lshl_b32 s20, s20, 8
	s_add_u32 s18, s10, s20
	s_addc_u32 s19, s11, 0
	global_load_dwordx4 v[98:101], v186, s[16:17]
	global_load_dwordx4 v[102:105], v187, s[16:17]
	global_load_dwordx4 v[106:109], v188, s[16:17]
	global_load_dwordx4 v[110:113], v189, s[16:17]
	global_load_dwordx4 v[114:117], v186, s[18:19]
	global_load_dwordx4 v[118:121], v187, s[18:19]
	global_load_dwordx4 v[122:125], v188, s[18:19]
	global_load_dwordx4 v[126:129], v189, s[18:19]
	s_lshl_b32 s20, s26, 11
	s_lshl_b32 s21, s28, 9
	s_add_i32 s21, s21, 0
	s_add_i32 s20, s20, s21
	s_add_u32 s16, s6, s20
	s_addc_u32 s17, s7, 0
	s_lshl_b32 s20, s27, 11
	s_add_i32 s20, s20, s21
	s_add_u32 s18, s12, s20
	s_addc_u32 s19, s13, 0
	global_load_dwordx4 v[130:133], v190, s[16:17]
	global_load_dwordx4 v[134:137], v191, s[16:17]
	global_load_dwordx4 v[138:141], v192, s[16:17]
	global_load_dwordx4 v[142:145], v193, s[16:17]
	global_load_dwordx4 v[146:149], v190, s[18:19]
	global_load_dwordx4 v[150:153], v191, s[18:19]
	global_load_dwordx4 v[154:157], v192, s[18:19]
	global_load_dwordx4 v[158:161], v193, s[18:19]
	s_waitcnt vmcnt(8)
	ds_write_b128 v194, v[98:101] offset:0
	ds_write_b128 v194, v[102:105] offset:8704
	ds_write_b128 v194, v[106:109] offset:17408
	ds_write_b128 v194, v[110:113] offset:26112
	ds_write_b128 v194, v[114:117] offset:34816
	ds_write_b128 v194, v[118:121] offset:43520
	ds_write_b128 v194, v[122:125] offset:52224
	ds_write_b128 v194, v[126:129] offset:60928
; #define MFMA32(a, b, c) __builtin_amdgcn_mfma_f32_32x32x16_bf16((a), (b), (c), 0, 0, 0)
; DI float fexp2(float x) { return __builtin_amdgcn_exp2f(x); }
; DI void mma21(f32x16 (&acc)[2], const bf16_t* sA, const bf16_t* sB, int wr, int wc, int r, int h) {
;     const bf16_t* a = sA + (wr * 64 + r) * LS + h * 8;
;     const bf16_t* b = sB + (wc * 32 + r) * LS + h * 8;
; #pragma unroll
;     for (int s = 0; s < 4; ++s) {
;         const bf16x8 a0 = *(const bf16x8*)(a + s * 16), a1 = *(const bf16x8*)(a + 32 * LS + s * 16);
;         const bf16x8 b0 = *(const bf16x8*)(b + s * 16);
;         acc[0] = MFMA32(a0, b0, acc[0]);
;         acc[1] = MFMA32(a1, b0, acc[1]);
;     }
; DI void phase4(const Params& p, int l, unsigned char* smem) {
;     ...
;     for (int it = 0; it < nmine; ++it) {
;         const int t = vb + it * G;
;         const int xcd = t & 7, j = t >> 3, m0 = (32 * xcd + (j >> 3)) * 128, c0 = (j & 7) * 128;
;         f32x16 mg[2];
; #pragma unroll
;         for (int i = 0; i < 16; ++i) { mg[0][i] = 0.f; mg[1][i] = 0.f; }
; #pragma unroll 1
;         for (int n = 0; n < 4; ++n) {
;             const int g0 = it * 24 + n * 6;
;             f32x16 g[2], y[2];
; #pragma unroll
;             for (int i = 0; i < 16; ++i) { g[0][i] = 0.f; g[1][i] = 0.f; y[0][i] = 0.f; y[1][i] = 0.f; }
;             __syncthreads(); mma21(g, sA, sB, wr, wc, r, h); stg4_commit(R1, sA + TILE_E, sB + TILE_E, srow, skc); ISS(R1, g0 + 3);
;             __syncthreads(); mma21(g, sA + TILE_E, sB + TILE_E, wr, wc, r, h); stg4_commit(R0, sA, sB, srow, skc); ISS(R0, g0 + 4);
; #pragma unroll
;             for (int mi = 0; mi < 2; ++mi)
; #pragma unroll
;                 for (int i = 0; i < 16; ++i) g[mi][i] = __builtin_amdgcn_rcpf(1.f + fexp2(-g[mi][i] * LOG2E));
;             __syncthreads(); mma21(y, sA, sB, wr, wc, r, h); stg4_commit(R1, sA + TILE_E, sB + TILE_E, srow, skc); ISS(R1, g0 + 5);
;             __syncthreads(); mma21(y, sA + TILE_E, sB + TILE_E, wr, wc, r, h); stg4_commit(R0, sA, sB, srow, skc); ISS(R0, g0 + 6);
;             __syncthreads(); mma21(y, sA, sB, wr, wc, r, h); stg4_commit(R1, sA + TILE_E, sB + TILE_E, srow, skc); ISS(R1, g0 + 7);
;             __syncthreads(); mma21(y, sA + TILE_E, sB + TILE_E, wr, wc, r, h); stg4_commit(R0, sA, sB, srow, skc); ISS(R0, g0 + 8);
.Lp4_body:
	s_add_i32 s29, s25, s78
	s_cmpk_lt_u32 s29, 0x800
	s_cselect_b32 s30, 1, 0
	s_waitcnt lgkmcnt(0)
	s_lshl_b32 s28, s24, 1
	s_add_i32 s28, s28, 0
	s_lshl_b32 s20, s26, 11
	s_lshl_b32 s21, s28, 9
	s_add_i32 s21, s21, 256
	s_add_i32 s20, s20, s21
	s_add_u32 s16, s6, s20
	s_addc_u32 s17, s7, 0
	s_lshl_b32 s20, s27, 11
	s_add_i32 s20, s20, s21
	s_add_u32 s18, s12, s20
	s_addc_u32 s19, s13, 0
	global_load_dwordx4 v[98:101], v190, s[16:17]
	global_load_dwordx4 v[102:105], v191, s[16:17]
	global_load_dwordx4 v[106:109], v192, s[16:17]
	global_load_dwordx4 v[110:113], v193, s[16:17]
	global_load_dwordx4 v[114:117], v190, s[18:19]
	global_load_dwordx4 v[118:121], v191, s[18:19]
	global_load_dwordx4 v[122:125], v192, s[18:19]
	global_load_dwordx4 v[126:129], v193, s[18:19]
	s_barrier
	ds_read_b128 v[162:165], v196 offset:0
	ds_read_b128 v[170:173], v198 offset:0
	ds_read_b128 v[166:169], v196 offset:8704
	ds_read_b128 v[174:177], v196 offset:32
	ds_read_b128 v[182:185], v198 offset:32
	ds_read_b128 v[178:181], v196 offset:8736
	s_waitcnt lgkmcnt(4)
	v_mfma_f32_32x32x16_bf16 v[2:17], v[162:165], v[170:173], 0
	s_waitcnt lgkmcnt(3)
	v_mfma_f32_32x32x16_bf16 v[18:33], v[166:169], v[170:173], 0
	ds_read_b128 v[162:165], v196 offset:64
	ds_read_b128 v[170:173], v198 offset:64
	ds_read_b128 v[166:169], v196 offset:8768
	s_waitcnt lgkmcnt(4)
	v_mfma_f32_32x32x16_bf16 v[2:17], v[174:177], v[182:185], v[2:17]
	s_waitcnt lgkmcnt(3)
	v_mfma_f32_32x32x16_bf16 v[18:33], v[178:181], v[182:185], v[18:33]
	ds_read_b128 v[174:177], v196 offset:96
	ds_read_b128 v[182:185], v198 offset:96
	ds_read_b128 v[178:181], v196 offset:8800
	s_waitcnt lgkmcnt(4)
	v_mfma_f32_32x32x16_bf16 v[2:17], v[162:165], v[170:173], v[2:17]
	s_waitcnt lgkmcnt(3)
	v_mfma_f32_32x32x16_bf16 v[18:33], v[166:169], v[170:173], v[18:33]
	ds_read_b128 v[162:165], v196 offset:128
	ds_read_b128 v[170:173], v198 offset:128
	ds_read_b128 v[166:169], v196 offset:8832
	s_waitcnt lgkmcnt(4)
	v_mfma_f32_32x32x16_bf16 v[2:17], v[174:177], v[182:185], v[2:17]
	s_waitcnt lgkmcnt(3)
	v_mfma_f32_32x32x16_bf16 v[18:33], v[178:181], v[182:185], v[18:33]
	ds_read_b128 v[174:177], v196 offset:160
	ds_read_b128 v[182:185], v198 offset:160
	ds_read_b128 v[178:181], v196 offset:8864
	s_waitcnt lgkmcnt(4)
	v_mfma_f32_32x32x16_bf16 v[2:17], v[162:165], v[170:173], v[2:17]
	s_waitcnt lgkmcnt(3)
	v_mfma_f32_32x32x16_bf16 v[18:33], v[166:169], v[170:173], v[18:33]
	ds_read_b128 v[162:165], v196 offset:192
	ds_read_b128 v[170:173], v198 offset:192
	ds_read_b128 v[166:169], v196 offset:8896
	s_waitcnt lgkmcnt(4)
	v_mfma_f32_32x32x16_bf16 v[2:17], v[174:177], v[182:185], v[2:17]
	s_waitcnt lgkmcnt(3)
	v_mfma_f32_32x32x16_bf16 v[18:33], v[178:181], v[182:185], v[18:33]
	ds_read_b128 v[174:177], v196 offset:224
	ds_read_b128 v[182:185], v198 offset:224
	ds_read_b128 v[178:181], v196 offset:8928
	s_waitcnt lgkmcnt(4)
	v_mfma_f32_32x32x16_bf16 v[2:17], v[162:165], v[170:173], v[2:17]
	s_waitcnt lgkmcnt(3)
	v_mfma_f32_32x32x16_bf16 v[18:33], v[166:169], v[170:173], v[18:33]
	s_waitcnt lgkmcnt(1)
	v_mfma_f32_32x32x16_bf16 v[2:17], v[174:177], v[182:185], v[2:17]
	s_waitcnt lgkmcnt(0)
	v_mfma_f32_32x32x16_bf16 v[18:33], v[178:181], v[182:185], v[18:33]
	s_waitcnt vmcnt(8)
	ds_write_b128 v195, v[130:133] offset:0
	ds_write_b128 v195, v[134:137] offset:8704
	ds_write_b128 v195, v[138:141] offset:17408
	ds_write_b128 v195, v[142:145] offset:26112
	ds_write_b128 v195, v[146:149] offset:34816
	ds_write_b128 v195, v[150:153] offset:43520
	ds_write_b128 v195, v[154:157] offset:52224
	ds_write_b128 v195, v[158:161] offset:60928
	s_waitcnt lgkmcnt(0)
	s_lshl_b32 s28, s24, 1
	s_add_i32 s28, s28, 1
	s_lshl_b32 s20, s26, 8
	s_add_u32 s16, s8, s20
	s_addc_u32 s17, s9, 0
	s_lshl_b32 s20, s28, 10
	s_add_i32 s20, s20, s27
	s_lshl_b32 s20, s20, 8
	s_add_u32 s18, s10, s20
	s_addc_u32 s19, s11, 0
	global_load_dwordx4 v[130:133], v186, s[16:17]
	global_load_dwordx4 v[134:137], v187, s[16:17]
	global_load_dwordx4 v[138:141], v188, s[16:17]
	global_load_dwordx4 v[142:145], v189, s[16:17]
	global_load_dwordx4 v[146:149], v186, s[18:19]
	global_load_dwordx4 v[150:153], v187, s[18:19]
	global_load_dwordx4 v[154:157], v188, s[18:19]
	global_load_dwordx4 v[158:161], v189, s[18:19]
	s_barrier
; #define MFMA32(a, b, c) __builtin_amdgcn_mfma_f32_32x32x16_bf16((a), (b), (c), 0, 0, 0)
; DI float fexp2(float x) { return __builtin_amdgcn_exp2f(x); }
; DI void mma21(f32x16 (&acc)[2], const bf16_t* sA, const bf16_t* sB, int wr, int wc, int r, int h) {
;     const bf16_t* a = sA + (wr * 64 + r) * LS + h * 8;
;     const bf16_t* b = sB + (wc * 32 + r) * LS + h * 8;
; #pragma unroll
;     for (int s = 0; s < 4; ++s) {
;         const bf16x8 a0 = *(const bf16x8*)(a + s * 16), a1 = *(const bf16x8*)(a + 32 * LS + s * 16);
;         const bf16x8 b0 = *(const bf16x8*)(b + s * 16);
;         acc[0] = MFMA32(a0, b0, acc[0]);
;         acc[1] = MFMA32(a1, b0, acc[1]);
;     }
; DI void phase4(const Params& p, int l, unsigned char* smem) {
;     ...
;             __syncthreads(); mma21(g, sA, sB, wr, wc, r, h); stg4_commit(R1, sA + TILE_E, sB + TILE_E, srow, skc); ISS(R1, g0 + 3);
;             __syncthreads(); mma21(g, sA + TILE_E, sB + TILE_E, wr, wc, r, h); stg4_commit(R0, sA, sB, srow, skc); ISS(R0, g0 + 4);
; #pragma unroll
;             for (int mi = 0; mi < 2; ++mi)
; #pragma unroll
;                 for (int i = 0; i < 16; ++i) g[mi][i] = __builtin_amdgcn_rcpf(1.f + fexp2(-g[mi][i] * LOG2E));
;             __syncthreads(); mma21(y, sA, sB, wr, wc, r, h); stg4_commit(R1, sA + TILE_E, sB + TILE_E, srow, skc); ISS(R1, g0 + 5);
;             __syncthreads(); mma21(y, sA + TILE_E, sB + TILE_E, wr, wc, r, h); stg4_commit(R0, sA, sB, srow, skc); ISS(R0, g0 + 6);
;             __syncthreads(); mma21(y, sA, sB, wr, wc, r, h); stg4_commit(R1, sA + TILE_E, sB + TILE_E, srow, skc); ISS(R1, g0 + 7);
;             __syncthreads(); mma21(y, sA + TILE_E, sB + TILE_E, wr, wc, r, h); stg4_commit(R0, sA, sB, srow, skc); ISS(R0, g0 + 8);
	ds_read_b128 v[162:165], v197 offset:0
	ds_read_b128 v[170:173], v199 offset:0
	ds_read_b128 v[166:169], v197 offset:8704
	ds_read_b128 v[174:177], v197 offset:32
	ds_read_b128 v[182:185], v199 offset:32
	ds_read_b128 v[178:181], v197 offset:8736
	s_waitcnt lgkmcnt(4)
	v_mfma_f32_32x32x16_bf16 v[34:49], v[162:165], v[170:173], 0
	s_waitcnt lgkmcnt(3)
	v_mfma_f32_32x32x16_bf16 v[50:65], v[166:169], v[170:173], 0
	ds_read_b128 v[162:165], v197 offset:64
	ds_read_b128 v[170:173], v199 offset:64
	ds_read_b128 v[166:169], v197 offset:8768
	s_waitcnt lgkmcnt(4)
	v_mfma_f32_32x32x16_bf16 v[34:49], v[174:177], v[182:185], v[34:49]
	s_waitcnt lgkmcnt(3)
	v_mfma_f32_32x32x16_bf16 v[50:65], v[178:181], v[182:185], v[50:65]
	ds_read_b128 v[174:177], v197 offset:96
	ds_read_b128 v[182:185], v199 offset:96
	ds_read_b128 v[178:181], v197 offset:8800
	s_waitcnt lgkmcnt(4)
	v_mfma_f32_32x32x16_bf16 v[34:49], v[162:165], v[170:173], v[34:49]
	s_waitcnt lgkmcnt(3)
	v_mfma_f32_32x32x16_bf16 v[50:65], v[166:169], v[170:173], v[50:65]
	ds_read_b128 v[162:165], v197 offset:128
	ds_read_b128 v[170:173], v199 offset:128
	ds_read_b128 v[166:169], v197 offset:8832
	s_waitcnt lgkmcnt(4)
	v_mfma_f32_32x32x16_bf16 v[34:49], v[174:177], v[182:185], v[34:49]
	s_waitcnt lgkmcnt(3)
	v_mfma_f32_32x32x16_bf16 v[50:65], v[178:181], v[182:185], v[50:65]
	ds_read_b128 v[174:177], v197 offset:160
	ds_read_b128 v[182:185], v199 offset:160
	ds_read_b128 v[178:181], v197 offset:8864
	s_waitcnt lgkmcnt(4)
	v_mfma_f32_32x32x16_bf16 v[34:49], v[162:165], v[170:173], v[34:49]
	s_waitcnt lgkmcnt(3)
	v_mfma_f32_32x32x16_bf16 v[50:65], v[166:169], v[170:173], v[50:65]
	ds_read_b128 v[162:165], v197 offset:192
	ds_read_b128 v[170:173], v199 offset:192
	ds_read_b128 v[166:169], v197 offset:8896
	s_waitcnt lgkmcnt(4)
	v_mfma_f32_32x32x16_bf16 v[34:49], v[174:177], v[182:185], v[34:49]
	s_waitcnt lgkmcnt(3)
	v_mfma_f32_32x32x16_bf16 v[50:65], v[178:181], v[182:185], v[50:65]
	ds_read_b128 v[174:177], v197 offset:224
	ds_read_b128 v[182:185], v199 offset:224
	ds_read_b128 v[178:181], v197 offset:8928
	s_waitcnt lgkmcnt(4)
	v_mfma_f32_32x32x16_bf16 v[34:49], v[162:165], v[170:173], v[34:49]
	s_waitcnt lgkmcnt(3)
	v_mfma_f32_32x32x16_bf16 v[50:65], v[166:169], v[170:173], v[50:65]
	s_waitcnt lgkmcnt(1)
	v_mfma_f32_32x32x16_bf16 v[34:49], v[174:177], v[182:185], v[34:49]
	s_waitcnt lgkmcnt(0)
	v_mfma_f32_32x32x16_bf16 v[50:65], v[178:181], v[182:185], v[50:65]
	s_waitcnt vmcnt(8)
	ds_write_b128 v194, v[98:101] offset:0
	ds_write_b128 v194, v[102:105] offset:8704
	ds_write_b128 v194, v[106:109] offset:17408
	ds_write_b128 v194, v[110:113] offset:26112
	ds_write_b128 v194, v[114:117] offset:34816
	ds_write_b128 v194, v[118:121] offset:43520
	ds_write_b128 v194, v[122:125] offset:52224
	ds_write_b128 v194, v[126:129] offset:60928
	s_waitcnt lgkmcnt(0)
	s_lshl_b32 s28, s24, 1
	s_add_i32 s28, s28, 1
	s_lshl_b32 s20, s26, 11
	s_lshl_b32 s21, s28, 9
	s_add_i32 s21, s21, 0
	s_add_i32 s20, s20, s21
	s_add_u32 s16, s6, s20
	s_addc_u32 s17, s7, 0
	s_lshl_b32 s20, s27, 11
	s_add_i32 s20, s20, s21
	s_add_u32 s18, s12, s20
	s_addc_u32 s19, s13, 0
	global_load_dwordx4 v[98:101], v190, s[16:17]
	global_load_dwordx4 v[102:105], v191, s[16:17]
	global_load_dwordx4 v[106:109], v192, s[16:17]
	global_load_dwordx4 v[110:113], v193, s[16:17]
	global_load_dwordx4 v[114:117], v190, s[18:19]
	global_load_dwordx4 v[118:121], v191, s[18:19]
	global_load_dwordx4 v[122:125], v192, s[18:19]
	global_load_dwordx4 v[126:129], v193, s[18:19]
	s_barrier
	ds_read_b128 v[162:165], v196 offset:0
	ds_read_b128 v[170:173], v198 offset:0
	ds_read_b128 v[166:169], v196 offset:8704
	ds_read_b128 v[174:177], v196 offset:32
	ds_read_b128 v[182:185], v198 offset:32
	ds_read_b128 v[178:181], v196 offset:8736
	s_waitcnt lgkmcnt(4)
	v_mfma_f32_32x32x16_bf16 v[34:49], v[162:165], v[170:173], v[34:49]
	s_waitcnt lgkmcnt(3)
	v_mfma_f32_32x32x16_bf16 v[50:65], v[166:169], v[170:173], v[50:65]
	ds_read_b128 v[162:165], v196 offset:64
	ds_read_b128 v[170:173], v198 offset:64
	ds_read_b128 v[166:169], v196 offset:8768
	s_waitcnt lgkmcnt(4)
	v_mfma_f32_32x32x16_bf16 v[34:49], v[174:177], v[182:185], v[34:49]
	s_waitcnt lgkmcnt(3)
	v_mfma_f32_32x32x16_bf16 v[50:65], v[178:181], v[182:185], v[50:65]
	ds_read_b128 v[174:177], v196 offset:96
	ds_read_b128 v[182:185], v198 offset:96
	ds_read_b128 v[178:181], v196 offset:8800
	s_waitcnt lgkmcnt(4)
	v_mfma_f32_32x32x16_bf16 v[34:49], v[162:165], v[170:173], v[34:49]
	s_waitcnt lgkmcnt(3)
	v_mfma_f32_32x32x16_bf16 v[50:65], v[166:169], v[170:173], v[50:65]
	ds_read_b128 v[162:165], v196 offset:128
	ds_read_b128 v[170:173], v198 offset:128
	ds_read_b128 v[166:169], v196 offset:8832
	s_waitcnt lgkmcnt(4)
	v_mfma_f32_32x32x16_bf16 v[34:49], v[174:177], v[182:185], v[34:49]
	s_waitcnt lgkmcnt(3)
	v_mfma_f32_32x32x16_bf16 v[50:65], v[178:181], v[182:185], v[50:65]
	ds_read_b128 v[174:177], v196 offset:160
	ds_read_b128 v[182:185], v198 offset:160
	ds_read_b128 v[178:181], v196 offset:8864
	s_waitcnt lgkmcnt(4)
	v_mfma_f32_32x32x16_bf16 v[34:49], v[162:165], v[170:173], v[34:49]
	s_waitcnt lgkmcnt(3)
	v_mfma_f32_32x32x16_bf16 v[50:65], v[166:169], v[170:173], v[50:65]
	ds_read_b128 v[162:165], v196 offset:192
	ds_read_b128 v[170:173], v198 offset:192
	ds_read_b128 v[166:169], v196 offset:8896
	s_waitcnt lgkmcnt(4)
	v_mfma_f32_32x32x16_bf16 v[34:49], v[174:177], v[182:185], v[34:49]
	s_waitcnt lgkmcnt(3)
	v_mfma_f32_32x32x16_bf16 v[50:65], v[178:181], v[182:185], v[50:65]
	ds_read_b128 v[174:177], v196 offset:224
	ds_read_b128 v[182:185], v198 offset:224
	ds_read_b128 v[178:181], v196 offset:8928
	s_waitcnt lgkmcnt(4)
; DI void phase4(const Params& p, int l, unsigned char* smem) {
;     ...
;     auto ISS = [&](Stg4& R, int g) {
;         g = g < gmax ? g : gmax;
;         const int i = g / 24, v = g - i * 24, n = v / 6, jj = v - n * 6;
;         const int t = vb + i * G, xcd = t & 7, j = t >> 3, m0 = (32 * xcd + (j >> 3)) * 128, c0 = (j & 7) * 128;
;         if (jj < 2) stg4_issue(R, MR + (size_t)m0 * 128 + jj * 64, o128, s128, WMU + (size_t)(n * 1024 + c0) * 128 + jj * 64, o128, s128);
;         else stg4_issue(R, YB + (size_t)m0 * 1024 + n * 256 + (jj - 2) * 64, o1024, s1024, WBR + (size_t)c0 * 1024 + n * 256 + (jj - 2) * 64, o1024, s1024);
;     };
;     Stg4 R0, R1;
;     ISS(R0, 0); ISS(R1, 1);
;     stg4_commit(R0, sA, sB, srow, skc);
;     ISS(R0, 2);
; #pragma unroll 1
;     for (int it = 0; it < nmine; ++it) {
;         const int t = vb + it * G;
;         const int xcd = t & 7, j = t >> 3, m0 = (32 * xcd + (j >> 3)) * 128, c0 = (j & 7) * 128;
;         f32x16 mg[2];
; #pragma unroll
;         for (int i = 0; i < 16; ++i) { mg[0][i] = 0.f; mg[1][i] = 0.f; }
; #pragma unroll 1
;         for (int n = 0; n < 4; ++n) {
;             const int g0 = it * 24 + n * 6;
;             f32x16 g[2], y[2];
; #pragma unroll
;             for (int i = 0; i < 16; ++i) { g[0][i] = 0.f; g[1][i] = 0.f; y[0][i] = 0.f; y[1][i] = 0.f; }
;             __syncthreads(); mma21(g, sA, sB, wr, wc, r, h); stg4_commit(R1, sA + TILE_E, sB + TILE_E, srow, skc); ISS(R1, g0 + 3);
;             __syncthreads(); mma21(g, sA + TILE_E, sB + TILE_E, wr, wc, r, h); stg4_commit(R0, sA, sB, srow, skc); ISS(R0, g0 + 4);
; #pragma unroll
;             for (int mi = 0; mi < 2; ++mi)
; #pragma unroll
;                 for (int i = 0; i < 16; ++i) g[mi][i] = __builtin_amdgcn_rcpf(1.f + fexp2(-g[mi][i] * LOG2E));
;             __syncthreads(); mma21(y, sA, sB, wr, wc, r, h); stg4_commit(R1, sA + TILE_E, sB + TILE_E, srow, skc); ISS(R1, g0 + 5);
;             __syncthreads(); mma21(y, sA + TILE_E, sB + TILE_E, wr, wc, r, h); stg4_commit(R0, sA, sB, srow, skc); ISS(R0, g0 + 6);
;             __syncthreads(); mma21(y, sA, sB, wr, wc, r, h); stg4_commit(R1, sA + TILE_E, sB + TILE_E, srow, skc); ISS(R1, g0 + 7);
;             __syncthreads(); mma21(y, sA + TILE_E, sB + TILE_E, wr, wc, r, h); stg4_commit(R0, sA, sB, srow, skc); ISS(R0, g0 + 8);
; #pragma unroll
;             for (int mi = 0; mi < 2; ++mi)
; #pragma unroll
	v_mfma_f32_32x32x16_bf16 v[34:49], v[162:165], v[170:173], v[34:49]
	s_waitcnt lgkmcnt(3)
	v_mfma_f32_32x32x16_bf16 v[50:65], v[166:169], v[170:173], v[50:65]
	s_waitcnt lgkmcnt(1)
	v_mfma_f32_32x32x16_bf16 v[34:49], v[174:177], v[182:185], v[34:49]
	s_waitcnt lgkmcnt(0)
	v_mfma_f32_32x32x16_bf16 v[50:65], v[178:181], v[182:185], v[50:65]
	s_waitcnt vmcnt(8)
	ds_write_b128 v195, v[130:133] offset:0
	ds_write_b128 v195, v[134:137] offset:8704
	ds_write_b128 v195, v[138:141] offset:17408
	ds_write_b128 v195, v[142:145] offset:26112
	ds_write_b128 v195, v[146:149] offset:34816
	ds_write_b128 v195, v[150:153] offset:43520
	ds_write_b128 v195, v[154:157] offset:52224
	ds_write_b128 v195, v[158:161] offset:60928
	s_nop 7
	s_nop 3
	v_mul_f32_e32 v2, 0xbfb8aa3b, v2
	v_mul_f32_e32 v3, 0xbfb8aa3b, v3
	v_mul_f32_e32 v4, 0xbfb8aa3b, v4
	v_mul_f32_e32 v5, 0xbfb8aa3b, v5
	v_mul_f32_e32 v6, 0xbfb8aa3b, v6
	v_mul_f32_e32 v7, 0xbfb8aa3b, v7
	v_mul_f32_e32 v8, 0xbfb8aa3b, v8
	v_mul_f32_e32 v9, 0xbfb8aa3b, v9
	v_exp_f32_e32 v2, v2
	v_exp_f32_e32 v3, v3
	v_exp_f32_e32 v4, v4
	v_exp_f32_e32 v5, v5
	v_exp_f32_e32 v6, v6
	v_exp_f32_e32 v7, v7
	v_exp_f32_e32 v8, v8
	v_exp_f32_e32 v9, v9
	v_add_f32_e32 v2, 1.0, v2
	v_add_f32_e32 v3, 1.0, v3
	v_add_f32_e32 v4, 1.0, v4
	v_add_f32_e32 v5, 1.0, v5
	v_add_f32_e32 v6, 1.0, v6
	v_add_f32_e32 v7, 1.0, v7
	v_add_f32_e32 v8, 1.0, v8
	v_add_f32_e32 v9, 1.0, v9
	v_rcp_f32_e32 v2, v2
	v_rcp_f32_e32 v3, v3
	v_rcp_f32_e32 v4, v4
	v_rcp_f32_e32 v5, v5
	v_rcp_f32_e32 v6, v6
	v_rcp_f32_e32 v7, v7
	v_rcp_f32_e32 v8, v8
	v_rcp_f32_e32 v9, v9
	v_fmac_f32_e32 v66, v2, v34
	v_fmac_f32_e32 v67, v3, v35
	v_fmac_f32_e32 v68, v4, v36
	v_fmac_f32_e32 v69, v5, v37
	v_fmac_f32_e32 v70, v6, v38
	v_fmac_f32_e32 v71, v7, v39
	v_fmac_f32_e32 v72, v8, v40
	v_fmac_f32_e32 v73, v9, v41
	v_mul_f32_e32 v10, 0xbfb8aa3b, v10
	v_mul_f32_e32 v11, 0xbfb8aa3b, v11
	v_mul_f32_e32 v12, 0xbfb8aa3b, v12
	v_mul_f32_e32 v13, 0xbfb8aa3b, v13
	v_mul_f32_e32 v14, 0xbfb8aa3b, v14
	v_mul_f32_e32 v15, 0xbfb8aa3b, v15
	v_mul_f32_e32 v16, 0xbfb8aa3b, v16
	v_mul_f32_e32 v17, 0xbfb8aa3b, v17
	v_exp_f32_e32 v10, v10
	v_exp_f32_e32 v11, v11
	v_exp_f32_e32 v12, v12
	v_exp_f32_e32 v13, v13
	v_exp_f32_e32 v14, v14
	v_exp_f32_e32 v15, v15
	v_exp_f32_e32 v16, v16
	v_exp_f32_e32 v17, v17
	v_add_f32_e32 v10, 1.0, v10
	v_add_f32_e32 v11, 1.0, v11
	v_add_f32_e32 v12, 1.0, v12
	v_add_f32_e32 v13, 1.0, v13
	v_add_f32_e32 v14, 1.0, v14
	v_add_f32_e32 v15, 1.0, v15
	v_add_f32_e32 v16, 1.0, v16
	v_add_f32_e32 v17, 1.0, v17
	v_rcp_f32_e32 v10, v10
	v_rcp_f32_e32 v11, v11
	v_rcp_f32_e32 v12, v12
	v_rcp_f32_e32 v13, v13
	v_rcp_f32_e32 v14, v14
	v_rcp_f32_e32 v15, v15
	v_rcp_f32_e32 v16, v16
	v_rcp_f32_e32 v17, v17
	v_fmac_f32_e32 v74, v10, v42
	v_fmac_f32_e32 v75, v11, v43
	v_fmac_f32_e32 v76, v12, v44
	v_fmac_f32_e32 v77, v13, v45
	v_fmac_f32_e32 v78, v14, v46
	v_fmac_f32_e32 v79, v15, v47
	v_fmac_f32_e32 v80, v16, v48
	v_fmac_f32_e32 v81, v17, v49
	v_mul_f32_e32 v18, 0xbfb8aa3b, v18
	v_mul_f32_e32 v19, 0xbfb8aa3b, v19
	v_mul_f32_e32 v20, 0xbfb8aa3b, v20
	v_mul_f32_e32 v21, 0xbfb8aa3b, v21
	v_mul_f32_e32 v22, 0xbfb8aa3b, v22
	v_mul_f32_e32 v23, 0xbfb8aa3b, v23
	v_mul_f32_e32 v24, 0xbfb8aa3b, v24
	v_mul_f32_e32 v25, 0xbfb8aa3b, v25
	v_exp_f32_e32 v18, v18
	v_exp_f32_e32 v19, v19
	v_exp_f32_e32 v20, v20
	v_exp_f32_e32 v21, v21
	v_exp_f32_e32 v22, v22
	v_exp_f32_e32 v23, v23
	v_exp_f32_e32 v24, v24
	v_exp_f32_e32 v25, v25
	v_add_f32_e32 v18, 1.0, v18
	v_add_f32_e32 v19, 1.0, v19
	v_add_f32_e32 v20, 1.0, v20
	v_add_f32_e32 v21, 1.0, v21
	v_add_f32_e32 v22, 1.0, v22
	v_add_f32_e32 v23, 1.0, v23
	v_add_f32_e32 v24, 1.0, v24
	v_add_f32_e32 v25, 1.0, v25
	v_rcp_f32_e32 v18, v18
	v_rcp_f32_e32 v19, v19
	v_rcp_f32_e32 v20, v20
	v_rcp_f32_e32 v21, v21
	v_rcp_f32_e32 v22, v22
	v_rcp_f32_e32 v23, v23
	v_rcp_f32_e32 v24, v24
	v_rcp_f32_e32 v25, v25
	v_fmac_f32_e32 v82, v18, v50
	v_fmac_f32_e32 v83, v19, v51
	v_fmac_f32_e32 v84, v20, v52
	v_fmac_f32_e32 v85, v21, v53
	v_fmac_f32_e32 v86, v22, v54
	v_fmac_f32_e32 v87, v23, v55
	v_fmac_f32_e32 v88, v24, v56
	v_fmac_f32_e32 v89, v25, v57
	v_mul_f32_e32 v26, 0xbfb8aa3b, v26
	v_mul_f32_e32 v27, 0xbfb8aa3b, v27
	v_mul_f32_e32 v28, 0xbfb8aa3b, v28
	v_mul_f32_e32 v29, 0xbfb8aa3b, v29
	v_mul_f32_e32 v30, 0xbfb8aa3b, v30
	v_mul_f32_e32 v31, 0xbfb8aa3b, v31
	v_mul_f32_e32 v32, 0xbfb8aa3b, v32
	v_mul_f32_e32 v33, 0xbfb8aa3b, v33
	v_exp_f32_e32 v26, v26
	v_exp_f32_e32 v27, v27
	v_exp_f32_e32 v28, v28
	v_exp_f32_e32 v29, v29
	v_exp_f32_e32 v30, v30
	v_exp_f32_e32 v31, v31
	v_exp_f32_e32 v32, v32
	v_exp_f32_e32 v33, v33
	v_add_f32_e32 v26, 1.0, v26
	v_add_f32_e32 v27, 1.0, v27
	v_add_f32_e32 v28, 1.0, v28
	v_add_f32_e32 v29, 1.0, v29
	v_add_f32_e32 v30, 1.0, v30
	v_add_f32_e32 v31, 1.0, v31
	v_add_f32_e32 v32, 1.0, v32
	v_add_f32_e32 v33, 1.0, v33
	v_rcp_f32_e32 v26, v26
	v_rcp_f32_e32 v27, v27
	v_rcp_f32_e32 v28, v28
	v_rcp_f32_e32 v29, v29
	v_rcp_f32_e32 v30, v30
	v_rcp_f32_e32 v31, v31
	v_rcp_f32_e32 v32, v32
	v_rcp_f32_e32 v33, v33
	v_fmac_f32_e32 v90, v26, v58
	v_fmac_f32_e32 v91, v27, v59
	v_fmac_f32_e32 v92, v28, v60
	v_fmac_f32_e32 v93, v29, v61
	v_fmac_f32_e32 v94, v30, v62
	v_fmac_f32_e32 v95, v31, v63
	v_fmac_f32_e32 v96, v32, v64
	v_fmac_f32_e32 v97, v33, v65
	s_waitcnt lgkmcnt(0)
	s_lshl_b32 s28, s24, 1
	s_add_i32 s28, s28, 1
	s_lshl_b32 s20, s26, 11
	s_lshl_b32 s21, s28, 9
	s_add_i32 s21, s21, 256
	s_add_i32 s20, s20, s21
	s_add_u32 s16, s6, s20
	s_addc_u32 s17, s7, 0
	s_lshl_b32 s20, s27, 11
	s_add_i32 s20, s20, s21
	s_add_u32 s18, s12, s20
	s_addc_u32 s19, s13, 0
	global_load_dwordx4 v[130:133], v190, s[16:17]
	global_load_dwordx4 v[134:137], v191, s[16:17]
	global_load_dwordx4 v[138:141], v192, s[16:17]
	global_load_dwordx4 v[142:145], v193, s[16:17]
	global_load_dwordx4 v[146:149], v190, s[18:19]
	global_load_dwordx4 v[150:153], v191, s[18:19]
	global_load_dwordx4 v[154:157], v192, s[18:19]
	global_load_dwordx4 v[158:161], v193, s[18:19]
	s_barrier
; DI void phase4(const Params& p, int l, unsigned char* smem) {
;     ...
;     auto ISS = [&](Stg4& R, int g) {
;         g = g < gmax ? g : gmax;
;         const int i = g / 24, v = g - i * 24, n = v / 6, jj = v - n * 6;
;         const int t = vb + i * G, xcd = t & 7, j = t >> 3, m0 = (32 * xcd + (j >> 3)) * 128, c0 = (j & 7) * 128;
;         if (jj < 2) stg4_issue(R, MR + (size_t)m0 * 128 + jj * 64, o128, s128, WMU + (size_t)(n * 1024 + c0) * 128 + jj * 64, o128, s128);
;         else stg4_issue(R, YB + (size_t)m0 * 1024 + n * 256 + (jj - 2) * 64, o1024, s1024, WBR + (size_t)c0 * 1024 + n * 256 + (jj - 2) * 64, o1024, s1024);
;     };
;     Stg4 R0, R1;
;     ISS(R0, 0); ISS(R1, 1);
;     stg4_commit(R0, sA, sB, srow, skc);
;     ISS(R0, 2);
; #pragma unroll 1
;     for (int it = 0; it < nmine; ++it) {
;         const int t = vb + it * G;
;         const int xcd = t & 7, j = t >> 3, m0 = (32 * xcd + (j >> 3)) * 128, c0 = (j & 7) * 128;
;         f32x16 mg[2];
; #pragma unroll
;         for (int i = 0; i < 16; ++i) { mg[0][i] = 0.f; mg[1][i] = 0.f; }
; #pragma unroll 1
;         for (int n = 0; n < 4; ++n) {
;             const int g0 = it * 24 + n * 6;
;             f32x16 g[2], y[2];
; #pragma unroll
;             for (int i = 0; i < 16; ++i) { g[0][i] = 0.f; g[1][i] = 0.f; y[0][i] = 0.f; y[1][i] = 0.f; }
;             __syncthreads(); mma21(g, sA, sB, wr, wc, r, h); stg4_commit(R1, sA + TILE_E, sB + TILE_E, srow, skc); ISS(R1, g0 + 3);
;             __syncthreads(); mma21(g, sA + TILE_E, sB + TILE_E, wr, wc, r, h); stg4_commit(R0, sA, sB, srow, skc); ISS(R0, g0 + 4);
	ds_read_b128 v[162:165], v197 offset:0
	ds_read_b128 v[170:173], v199 offset:0
	ds_read_b128 v[166:169], v197 offset:8704
	ds_read_b128 v[174:177], v197 offset:32
	ds_read_b128 v[182:185], v199 offset:32
	ds_read_b128 v[178:181], v197 offset:8736
	s_waitcnt lgkmcnt(4)
	v_mfma_f32_32x32x16_bf16 v[2:17], v[162:165], v[170:173], 0
	s_waitcnt lgkmcnt(3)
	v_mfma_f32_32x32x16_bf16 v[18:33], v[166:169], v[170:173], 0
	ds_read_b128 v[162:165], v197 offset:64
	ds_read_b128 v[170:173], v199 offset:64
	ds_read_b128 v[166:169], v197 offset:8768
	s_waitcnt lgkmcnt(4)
	v_mfma_f32_32x32x16_bf16 v[2:17], v[174:177], v[182:185], v[2:17]
	s_waitcnt lgkmcnt(3)
	v_mfma_f32_32x32x16_bf16 v[18:33], v[178:181], v[182:185], v[18:33]
	ds_read_b128 v[174:177], v197 offset:96
	ds_read_b128 v[182:185], v199 offset:96
	ds_read_b128 v[178:181], v197 offset:8800
	s_waitcnt lgkmcnt(4)
	v_mfma_f32_32x32x16_bf16 v[2:17], v[162:165], v[170:173], v[2:17]
	s_waitcnt lgkmcnt(3)
	v_mfma_f32_32x32x16_bf16 v[18:33], v[166:169], v[170:173], v[18:33]
	ds_read_b128 v[162:165], v197 offset:128
	ds_read_b128 v[170:173], v199 offset:128
	ds_read_b128 v[166:169], v197 offset:8832
	s_waitcnt lgkmcnt(4)
	v_mfma_f32_32x32x16_bf16 v[2:17], v[174:177], v[182:185], v[2:17]
	s_waitcnt lgkmcnt(3)
	v_mfma_f32_32x32x16_bf16 v[18:33], v[178:181], v[182:185], v[18:33]
	ds_read_b128 v[174:177], v197 offset:160
	ds_read_b128 v[182:185], v199 offset:160
	ds_read_b128 v[178:181], v197 offset:8864
	s_waitcnt lgkmcnt(4)
	v_mfma_f32_32x32x16_bf16 v[2:17], v[162:165], v[170:173], v[2:17]
	s_waitcnt lgkmcnt(3)
	v_mfma_f32_32x32x16_bf16 v[18:33], v[166:169], v[170:173], v[18:33]
	ds_read_b128 v[162:165], v197 offset:192
	ds_read_b128 v[170:173], v199 offset:192
	ds_read_b128 v[166:169], v197 offset:8896
	s_waitcnt lgkmcnt(4)
	v_mfma_f32_32x32x16_bf16 v[2:17], v[174:177], v[182:185], v[2:17]
	s_waitcnt lgkmcnt(3)
	v_mfma_f32_32x32x16_bf16 v[18:33], v[178:181], v[182:185], v[18:33]
	ds_read_b128 v[174:177], v197 offset:224
	ds_read_b128 v[182:185], v199 offset:224
	ds_read_b128 v[178:181], v197 offset:8928
	s_waitcnt lgkmcnt(4)
	v_mfma_f32_32x32x16_bf16 v[2:17], v[162:165], v[170:173], v[2:17]
	s_waitcnt lgkmcnt(3)
	v_mfma_f32_32x32x16_bf16 v[18:33], v[166:169], v[170:173], v[18:33]
	s_waitcnt lgkmcnt(1)
	v_mfma_f32_32x32x16_bf16 v[2:17], v[174:177], v[182:185], v[2:17]
	s_waitcnt lgkmcnt(0)
	v_mfma_f32_32x32x16_bf16 v[18:33], v[178:181], v[182:185], v[18:33]
	s_waitcnt vmcnt(8)
	ds_write_b128 v194, v[98:101] offset:0
	ds_write_b128 v194, v[102:105] offset:8704
	ds_write_b128 v194, v[106:109] offset:17408
	ds_write_b128 v194, v[110:113] offset:26112
	ds_write_b128 v194, v[114:117] offset:34816
	ds_write_b128 v194, v[118:121] offset:43520
	ds_write_b128 v194, v[122:125] offset:52224
	ds_write_b128 v194, v[126:129] offset:60928
	s_waitcnt lgkmcnt(0)
	s_cmp_eq_u32 s24, 0
	s_cbranch_scc1 .Lp4_pf_same_4
	s_cmp_eq_u32 s30, 0
	s_cbranch_scc1 .Lp4_pf_done_4
	s_and_b32 s20, s29, 7
	s_lshl_b32 s20, s20, 5
	s_lshr_b32 s21, s29, 6
	s_add_i32 s20, s20, s21
	s_lshl_b32 s22, s20, 7
	s_bfe_u32 s20, s29, 0x30003
	s_lshl_b32 s23, s20, 7
	s_mov_b32 s28, 0
	s_lshl_b32 s20, s22, 8
	s_add_u32 s16, s8, s20
	s_addc_u32 s17, s9, 0
	s_lshl_b32 s20, s28, 10
	s_add_i32 s20, s20, s23
	s_lshl_b32 s20, s20, 8
	s_add_u32 s18, s10, s20
	s_addc_u32 s19, s11, 0
	global_load_dwordx4 v[98:101], v186, s[16:17]
	global_load_dwordx4 v[102:105], v187, s[16:17]
	global_load_dwordx4 v[106:109], v188, s[16:17]
	global_load_dwordx4 v[110:113], v189, s[16:17]
	global_load_dwordx4 v[114:117], v186, s[18:19]
	global_load_dwordx4 v[118:121], v187, s[18:19]
	global_load_dwordx4 v[122:125], v188, s[18:19]
	global_load_dwordx4 v[126:129], v189, s[18:19]
	s_branch .Lp4_pf_done_4
.Lp4_pf_same_4:
	s_mov_b32 s28, 2
	s_lshl_b32 s20, s26, 8
	s_add_u32 s16, s8, s20
	s_addc_u32 s17, s9, 0
	s_lshl_b32 s20, s28, 10
	s_add_i32 s20, s20, s27
	s_lshl_b32 s20, s20, 8
	s_add_u32 s18, s10, s20
	s_addc_u32 s19, s11, 0
	global_load_dwordx4 v[98:101], v186, s[16:17]
	global_load_dwordx4 v[102:105], v187, s[16:17]
	global_load_dwordx4 v[106:109], v188, s[16:17]
	global_load_dwordx4 v[110:113], v189, s[16:17]
	global_load_dwordx4 v[114:117], v186, s[18:19]
	global_load_dwordx4 v[118:121], v187, s[18:19]
	global_load_dwordx4 v[122:125], v188, s[18:19]
	global_load_dwordx4 v[126:129], v189, s[18:19]
; DI float fexp2(float x) { return __builtin_amdgcn_exp2f(x); }
; DI void phase4(const Params& p, int l, unsigned char* smem) {
;     ...
;     auto ISS = [&](Stg4& R, int g) {
;         g = g < gmax ? g : gmax;
;         const int i = g / 24, v = g - i * 24, n = v / 6, jj = v - n * 6;
;         const int t = vb + i * G, xcd = t & 7, j = t >> 3, m0 = (32 * xcd + (j >> 3)) * 128, c0 = (j & 7) * 128;
;         if (jj < 2) stg4_issue(R, MR + (size_t)m0 * 128 + jj * 64, o128, s128, WMU + (size_t)(n * 1024 + c0) * 128 + jj * 64, o128, s128);
;         else stg4_issue(R, YB + (size_t)m0 * 1024 + n * 256 + (jj - 2) * 64, o1024, s1024, WBR + (size_t)c0 * 1024 + n * 256 + (jj - 2) * 64, o1024, s1024);
;     };
;     Stg4 R0, R1;
;     ISS(R0, 0); ISS(R1, 1);
;     stg4_commit(R0, sA, sB, srow, skc);
;     ISS(R0, 2);
; #pragma unroll 1
;     for (int it = 0; it < nmine; ++it) {
;         const int t = vb + it * G;
;         const int xcd = t & 7, j = t >> 3, m0 = (32 * xcd + (j >> 3)) * 128, c0 = (j & 7) * 128;
;         f32x16 mg[2];
; #pragma unroll
;         for (int i = 0; i < 16; ++i) { mg[0][i] = 0.f; mg[1][i] = 0.f; }
; #pragma unroll 1
;         for (int n = 0; n < 4; ++n) {
;             const int g0 = it * 24 + n * 6;
;             f32x16 g[2], y[2];
; #pragma unroll
;             for (int i = 0; i < 16; ++i) { g[0][i] = 0.f; g[1][i] = 0.f; y[0][i] = 0.f; y[1][i] = 0.f; }
;             __syncthreads(); mma21(g, sA, sB, wr, wc, r, h); stg4_commit(R1, sA + TILE_E, sB + TILE_E, srow, skc); ISS(R1, g0 + 3);
;             __syncthreads(); mma21(g, sA + TILE_E, sB + TILE_E, wr, wc, r, h); stg4_commit(R0, sA, sB, srow, skc); ISS(R0, g0 + 4);
; #pragma unroll
;             for (int mi = 0; mi < 2; ++mi)
; #pragma unroll
;                 for (int i = 0; i < 16; ++i) g[mi][i] = __builtin_amdgcn_rcpf(1.f + fexp2(-g[mi][i] * LOG2E));
;             __syncthreads(); mma21(y, sA, sB, wr, wc, r, h); stg4_commit(R1, sA + TILE_E, sB + TILE_E, srow, skc); ISS(R1, g0 + 5);
;             __syncthreads(); mma21(y, sA + TILE_E, sB + TILE_E, wr, wc, r, h); stg4_commit(R0, sA, sB, srow, skc); ISS(R0, g0 + 6);
;             __syncthreads(); mma21(y, sA, sB, wr, wc, r, h); stg4_commit(R1, sA + TILE_E, sB + TILE_E, srow, skc); ISS(R1, g0 + 7);
;             __syncthreads(); mma21(y, sA + TILE_E, sB + TILE_E, wr, wc, r, h); stg4_commit(R0, sA, sB, srow, skc); ISS(R0, g0 + 8);
.Lp4_pf_done_4:
	s_barrier
	ds_read_b128 v[162:165], v196 offset:0
	ds_read_b128 v[170:173], v198 offset:0
	ds_read_b128 v[166:169], v196 offset:8704
	ds_read_b128 v[174:177], v196 offset:32
	ds_read_b128 v[182:185], v198 offset:32
	ds_read_b128 v[178:181], v196 offset:8736
	s_waitcnt lgkmcnt(4)
	v_mfma_f32_32x32x16_bf16 v[34:49], v[162:165], v[170:173], 0
	s_waitcnt lgkmcnt(3)
	v_mfma_f32_32x32x16_bf16 v[50:65], v[166:169], v[170:173], 0
	ds_read_b128 v[162:165], v196 offset:64
	ds_read_b128 v[170:173], v198 offset:64
	ds_read_b128 v[166:169], v196 offset:8768
	s_waitcnt lgkmcnt(4)
	v_mfma_f32_32x32x16_bf16 v[34:49], v[174:177], v[182:185], v[34:49]
	s_waitcnt lgkmcnt(3)
	v_mfma_f32_32x32x16_bf16 v[50:65], v[178:181], v[182:185], v[50:65]
	ds_read_b128 v[174:177], v196 offset:96
	ds_read_b128 v[182:185], v198 offset:96
	ds_read_b128 v[178:181], v196 offset:8800
	s_waitcnt lgkmcnt(4)
	v_mfma_f32_32x32x16_bf16 v[34:49], v[162:165], v[170:173], v[34:49]
	s_waitcnt lgkmcnt(3)
	v_mfma_f32_32x32x16_bf16 v[50:65], v[166:169], v[170:173], v[50:65]
	ds_read_b128 v[162:165], v196 offset:128
	ds_read_b128 v[170:173], v198 offset:128
	ds_read_b128 v[166:169], v196 offset:8832
	s_waitcnt lgkmcnt(4)
	v_mfma_f32_32x32x16_bf16 v[34:49], v[174:177], v[182:185], v[34:49]
	s_waitcnt lgkmcnt(3)
	v_mfma_f32_32x32x16_bf16 v[50:65], v[178:181], v[182:185], v[50:65]
	ds_read_b128 v[174:177], v196 offset:160
	ds_read_b128 v[182:185], v198 offset:160
	ds_read_b128 v[178:181], v196 offset:8864
	s_waitcnt lgkmcnt(4)
	v_mfma_f32_32x32x16_bf16 v[34:49], v[162:165], v[170:173], v[34:49]
	s_waitcnt lgkmcnt(3)
	v_mfma_f32_32x32x16_bf16 v[50:65], v[166:169], v[170:173], v[50:65]
	ds_read_b128 v[162:165], v196 offset:192
	ds_read_b128 v[170:173], v198 offset:192
	ds_read_b128 v[166:169], v196 offset:8896
	s_waitcnt lgkmcnt(4)
	v_mfma_f32_32x32x16_bf16 v[34:49], v[174:177], v[182:185], v[34:49]
	s_waitcnt lgkmcnt(3)
	v_mfma_f32_32x32x16_bf16 v[50:65], v[178:181], v[182:185], v[50:65]
	ds_read_b128 v[174:177], v196 offset:224
	ds_read_b128 v[182:185], v198 offset:224
	ds_read_b128 v[178:181], v196 offset:8928
	s_waitcnt lgkmcnt(4)
	v_mfma_f32_32x32x16_bf16 v[34:49], v[162:165], v[170:173], v[34:49]
	s_waitcnt lgkmcnt(3)
	v_mfma_f32_32x32x16_bf16 v[50:65], v[166:169], v[170:173], v[50:65]
	s_waitcnt lgkmcnt(1)
	v_mfma_f32_32x32x16_bf16 v[34:49], v[174:177], v[182:185], v[34:49]
	s_waitcnt lgkmcnt(0)
	v_mfma_f32_32x32x16_bf16 v[50:65], v[178:181], v[182:185], v[50:65]
	s_cmp_eq_u32 s24, 0
	s_cbranch_scc1 .Lp4_w8_4
	s_cmp_eq_u32 s30, 0
	s_cbranch_scc0 .Lp4_w8_4
	s_waitcnt vmcnt(0)
	ds_write_b128 v195, v[130:133] offset:0
	ds_write_b128 v195, v[134:137] offset:8704
	ds_write_b128 v195, v[138:141] offset:17408
	ds_write_b128 v195, v[142:145] offset:26112
	ds_write_b128 v195, v[146:149] offset:34816
	ds_write_b128 v195, v[150:153] offset:43520
	ds_write_b128 v195, v[154:157] offset:52224
	ds_write_b128 v195, v[158:161] offset:60928
	s_branch .Lp4_wd_4
.Lp4_w8_4:
	s_waitcnt vmcnt(8)
	ds_write_b128 v195, v[130:133] offset:0
	ds_write_b128 v195, v[134:137] offset:8704
	ds_write_b128 v195, v[138:141] offset:17408
	ds_write_b128 v195, v[142:145] offset:26112
	ds_write_b128 v195, v[146:149] offset:34816
	ds_write_b128 v195, v[150:153] offset:43520
	ds_write_b128 v195, v[154:157] offset:52224
	ds_write_b128 v195, v[158:161] offset:60928
.Lp4_wd_4:
	s_waitcnt lgkmcnt(0)
	s_cmp_eq_u32 s24, 0
	s_cbranch_scc1 .Lp4_pf_same_5
	s_cmp_eq_u32 s30, 0
	s_cbranch_scc1 .Lp4_pf_done_5
	s_and_b32 s20, s29, 7
	s_lshl_b32 s20, s20, 5
	s_lshr_b32 s21, s29, 6
	s_add_i32 s20, s20, s21
	s_lshl_b32 s22, s20, 7
	s_bfe_u32 s20, s29, 0x30003
	s_lshl_b32 s23, s20, 7
	s_mov_b32 s28, 0
	s_lshl_b32 s20, s22, 11
	s_lshl_b32 s21, s28, 9
	s_add_i32 s21, s21, 0
	s_add_i32 s20, s20, s21
	s_add_u32 s16, s6, s20
	s_addc_u32 s17, s7, 0
	s_lshl_b32 s20, s23, 11
	s_add_i32 s20, s20, s21
	s_add_u32 s18, s12, s20
	s_addc_u32 s19, s13, 0
	global_load_dwordx4 v[130:133], v190, s[16:17]
	global_load_dwordx4 v[134:137], v191, s[16:17]
	global_load_dwordx4 v[138:141], v192, s[16:17]
	global_load_dwordx4 v[142:145], v193, s[16:17]
	global_load_dwordx4 v[146:149], v190, s[18:19]
	global_load_dwordx4 v[150:153], v191, s[18:19]
	global_load_dwordx4 v[154:157], v192, s[18:19]
	global_load_dwordx4 v[158:161], v193, s[18:19]
	s_branch .Lp4_pf_done_5
.Lp4_pf_same_5:
	s_mov_b32 s28, 2
	s_lshl_b32 s20, s26, 11
	s_lshl_b32 s21, s28, 9
	s_add_i32 s21, s21, 0
	s_add_i32 s20, s20, s21
	s_add_u32 s16, s6, s20
	s_addc_u32 s17, s7, 0
	s_lshl_b32 s20, s27, 11
	s_add_i32 s20, s20, s21
	s_add_u32 s18, s12, s20
	s_addc_u32 s19, s13, 0
	global_load_dwordx4 v[130:133], v190, s[16:17]
	global_load_dwordx4 v[134:137], v191, s[16:17]
	global_load_dwordx4 v[138:141], v192, s[16:17]
	global_load_dwordx4 v[142:145], v193, s[16:17]
	global_load_dwordx4 v[146:149], v190, s[18:19]
	global_load_dwordx4 v[150:153], v191, s[18:19]
	global_load_dwordx4 v[154:157], v192, s[18:19]
	global_load_dwordx4 v[158:161], v193, s[18:19]
; DI float fexp2(float x) { return __builtin_amdgcn_exp2f(x); }
; DI void phase4(const Params& p, int l, unsigned char* smem) {
;     ...
;             __syncthreads(); mma21(g, sA, sB, wr, wc, r, h); stg4_commit(R1, sA + TILE_E, sB + TILE_E, srow, skc); ISS(R1, g0 + 3);
;             __syncthreads(); mma21(g, sA + TILE_E, sB + TILE_E, wr, wc, r, h); stg4_commit(R0, sA, sB, srow, skc); ISS(R0, g0 + 4);
; #pragma unroll
;             for (int mi = 0; mi < 2; ++mi)
; #pragma unroll
;                 for (int i = 0; i < 16; ++i) g[mi][i] = __builtin_amdgcn_rcpf(1.f + fexp2(-g[mi][i] * LOG2E));
;             __syncthreads(); mma21(y, sA, sB, wr, wc, r, h); stg4_commit(R1, sA + TILE_E, sB + TILE_E, srow, skc); ISS(R1, g0 + 5);
;             __syncthreads(); mma21(y, sA + TILE_E, sB + TILE_E, wr, wc, r, h); stg4_commit(R0, sA, sB, srow, skc); ISS(R0, g0 + 6);
;             __syncthreads(); mma21(y, sA, sB, wr, wc, r, h); stg4_commit(R1, sA + TILE_E, sB + TILE_E, srow, skc); ISS(R1, g0 + 7);
;             __syncthreads(); mma21(y, sA + TILE_E, sB + TILE_E, wr, wc, r, h); stg4_commit(R0, sA, sB, srow, skc); ISS(R0, g0 + 8);
; #pragma unroll
;             for (int mi = 0; mi < 2; ++mi)
; #pragma unroll
;                 for (int i = 0; i < 16; ++i) mg[mi][i] += g[mi][i] * y[mi][i];
.Lp4_pf_done_5:
	s_barrier
	ds_read_b128 v[162:165], v197 offset:0
	ds_read_b128 v[170:173], v199 offset:0
	ds_read_b128 v[166:169], v197 offset:8704
	ds_read_b128 v[174:177], v197 offset:32
	ds_read_b128 v[182:185], v199 offset:32
	ds_read_b128 v[178:181], v197 offset:8736
	s_waitcnt lgkmcnt(4)
	v_mfma_f32_32x32x16_bf16 v[34:49], v[162:165], v[170:173], v[34:49]
	s_waitcnt lgkmcnt(3)
	v_mfma_f32_32x32x16_bf16 v[50:65], v[166:169], v[170:173], v[50:65]
	ds_read_b128 v[162:165], v197 offset:64
	ds_read_b128 v[170:173], v199 offset:64
	ds_read_b128 v[166:169], v197 offset:8768
	s_waitcnt lgkmcnt(4)
	v_mfma_f32_32x32x16_bf16 v[34:49], v[174:177], v[182:185], v[34:49]
	s_waitcnt lgkmcnt(3)
	v_mfma_f32_32x32x16_bf16 v[50:65], v[178:181], v[182:185], v[50:65]
	ds_read_b128 v[174:177], v197 offset:96
	ds_read_b128 v[182:185], v199 offset:96
	ds_read_b128 v[178:181], v197 offset:8800
	s_waitcnt lgkmcnt(4)
	v_mfma_f32_32x32x16_bf16 v[34:49], v[162:165], v[170:173], v[34:49]
	s_waitcnt lgkmcnt(3)
	v_mfma_f32_32x32x16_bf16 v[50:65], v[166:169], v[170:173], v[50:65]
	ds_read_b128 v[162:165], v197 offset:128
	ds_read_b128 v[170:173], v199 offset:128
	ds_read_b128 v[166:169], v197 offset:8832
	s_waitcnt lgkmcnt(4)
	v_mfma_f32_32x32x16_bf16 v[34:49], v[174:177], v[182:185], v[34:49]
	s_waitcnt lgkmcnt(3)
	v_mfma_f32_32x32x16_bf16 v[50:65], v[178:181], v[182:185], v[50:65]
	ds_read_b128 v[174:177], v197 offset:160
	ds_read_b128 v[182:185], v199 offset:160
	ds_read_b128 v[178:181], v197 offset:8864
	s_waitcnt lgkmcnt(4)
	v_mfma_f32_32x32x16_bf16 v[34:49], v[162:165], v[170:173], v[34:49]
	s_waitcnt lgkmcnt(3)
	v_mfma_f32_32x32x16_bf16 v[50:65], v[166:169], v[170:173], v[50:65]
	ds_read_b128 v[162:165], v197 offset:192
	ds_read_b128 v[170:173], v199 offset:192
	ds_read_b128 v[166:169], v197 offset:8896
	s_waitcnt lgkmcnt(4)
	v_mfma_f32_32x32x16_bf16 v[34:49], v[174:177], v[182:185], v[34:49]
	s_waitcnt lgkmcnt(3)
	v_mfma_f32_32x32x16_bf16 v[50:65], v[178:181], v[182:185], v[50:65]
	ds_read_b128 v[174:177], v197 offset:224
	ds_read_b128 v[182:185], v199 offset:224
	ds_read_b128 v[178:181], v197 offset:8928
	s_waitcnt lgkmcnt(4)
	v_mfma_f32_32x32x16_bf16 v[34:49], v[162:165], v[170:173], v[34:49]
	s_waitcnt lgkmcnt(3)
	v_mfma_f32_32x32x16_bf16 v[50:65], v[166:169], v[170:173], v[50:65]
	s_waitcnt lgkmcnt(1)
	v_mfma_f32_32x32x16_bf16 v[34:49], v[174:177], v[182:185], v[34:49]
	s_waitcnt lgkmcnt(0)
	v_mfma_f32_32x32x16_bf16 v[50:65], v[178:181], v[182:185], v[50:65]
	s_cmp_eq_u32 s24, 0
	s_cbranch_scc1 .Lp4_w8_5
	s_cmp_eq_u32 s30, 0
	s_cbranch_scc0 .Lp4_w8_5
	s_branch .Lp4_wd_5
.Lp4_w8_5:
	s_waitcnt vmcnt(8)
	ds_write_b128 v194, v[98:101] offset:0
	ds_write_b128 v194, v[102:105] offset:8704
	ds_write_b128 v194, v[106:109] offset:17408
	ds_write_b128 v194, v[110:113] offset:26112
	ds_write_b128 v194, v[114:117] offset:34816
	ds_write_b128 v194, v[118:121] offset:43520
	ds_write_b128 v194, v[122:125] offset:52224
	ds_write_b128 v194, v[126:129] offset:60928
.Lp4_wd_5:
	s_nop 7
	s_nop 3
	v_mul_f32_e32 v2, 0xbfb8aa3b, v2
	v_mul_f32_e32 v3, 0xbfb8aa3b, v3
	v_mul_f32_e32 v4, 0xbfb8aa3b, v4
	v_mul_f32_e32 v5, 0xbfb8aa3b, v5
	v_mul_f32_e32 v6, 0xbfb8aa3b, v6
	v_mul_f32_e32 v7, 0xbfb8aa3b, v7
	v_mul_f32_e32 v8, 0xbfb8aa3b, v8
	v_mul_f32_e32 v9, 0xbfb8aa3b, v9
	v_exp_f32_e32 v2, v2
	v_exp_f32_e32 v3, v3
	v_exp_f32_e32 v4, v4
	v_exp_f32_e32 v5, v5
	v_exp_f32_e32 v6, v6
	v_exp_f32_e32 v7, v7
	v_exp_f32_e32 v8, v8
	v_exp_f32_e32 v9, v9
	v_add_f32_e32 v2, 1.0, v2
	v_add_f32_e32 v3, 1.0, v3
	v_add_f32_e32 v4, 1.0, v4
	v_add_f32_e32 v5, 1.0, v5
	v_add_f32_e32 v6, 1.0, v6
	v_add_f32_e32 v7, 1.0, v7
	v_add_f32_e32 v8, 1.0, v8
	v_add_f32_e32 v9, 1.0, v9
	v_rcp_f32_e32 v2, v2
	v_rcp_f32_e32 v3, v3
	v_rcp_f32_e32 v4, v4
	v_rcp_f32_e32 v5, v5
	v_rcp_f32_e32 v6, v6
	v_rcp_f32_e32 v7, v7
	v_rcp_f32_e32 v8, v8
	v_rcp_f32_e32 v9, v9
	v_fmac_f32_e32 v66, v2, v34
	v_fmac_f32_e32 v67, v3, v35
	v_fmac_f32_e32 v68, v4, v36
	v_fmac_f32_e32 v69, v5, v37
	v_fmac_f32_e32 v70, v6, v38
	v_fmac_f32_e32 v71, v7, v39
	v_fmac_f32_e32 v72, v8, v40
	v_fmac_f32_e32 v73, v9, v41
	v_mul_f32_e32 v10, 0xbfb8aa3b, v10
	v_mul_f32_e32 v11, 0xbfb8aa3b, v11
	v_mul_f32_e32 v12, 0xbfb8aa3b, v12
	v_mul_f32_e32 v13, 0xbfb8aa3b, v13
	v_mul_f32_e32 v14, 0xbfb8aa3b, v14
	v_mul_f32_e32 v15, 0xbfb8aa3b, v15
	v_mul_f32_e32 v16, 0xbfb8aa3b, v16
	v_mul_f32_e32 v17, 0xbfb8aa3b, v17
	v_exp_f32_e32 v10, v10
	v_exp_f32_e32 v11, v11
	v_exp_f32_e32 v12, v12
	v_exp_f32_e32 v13, v13
	v_exp_f32_e32 v14, v14
	v_exp_f32_e32 v15, v15
	v_exp_f32_e32 v16, v16
	v_exp_f32_e32 v17, v17
	v_add_f32_e32 v10, 1.0, v10
	v_add_f32_e32 v11, 1.0, v11
	v_add_f32_e32 v12, 1.0, v12
	v_add_f32_e32 v13, 1.0, v13
	v_add_f32_e32 v14, 1.0, v14
	v_add_f32_e32 v15, 1.0, v15
	v_add_f32_e32 v16, 1.0, v16
	v_add_f32_e32 v17, 1.0, v17
	v_rcp_f32_e32 v10, v10
	v_rcp_f32_e32 v11, v11
	v_rcp_f32_e32 v12, v12
	v_rcp_f32_e32 v13, v13
	v_rcp_f32_e32 v14, v14
	v_rcp_f32_e32 v15, v15
	v_rcp_f32_e32 v16, v16
	v_rcp_f32_e32 v17, v17
	v_fmac_f32_e32 v74, v10, v42
	v_fmac_f32_e32 v75, v11, v43
	v_fmac_f32_e32 v76, v12, v44
	v_fmac_f32_e32 v77, v13, v45
	v_fmac_f32_e32 v78, v14, v46
	v_fmac_f32_e32 v79, v15, v47
	v_fmac_f32_e32 v80, v16, v48
	v_fmac_f32_e32 v81, v17, v49
	v_mul_f32_e32 v18, 0xbfb8aa3b, v18
	v_mul_f32_e32 v19, 0xbfb8aa3b, v19
	v_mul_f32_e32 v20, 0xbfb8aa3b, v20
	v_mul_f32_e32 v21, 0xbfb8aa3b, v21
	v_mul_f32_e32 v22, 0xbfb8aa3b, v22
	v_mul_f32_e32 v23, 0xbfb8aa3b, v23
	v_mul_f32_e32 v24, 0xbfb8aa3b, v24
	v_mul_f32_e32 v25, 0xbfb8aa3b, v25
	v_exp_f32_e32 v18, v18
	v_exp_f32_e32 v19, v19
	v_exp_f32_e32 v20, v20
	v_exp_f32_e32 v21, v21
	v_exp_f32_e32 v22, v22
; DI bf16_t tobf(float a) { return (bf16_t)(pk2(a, 0.f) & 0xffffu); }
; DI void phase4(const Params& p, int l, unsigned char* smem) {
;     ...
; #pragma unroll 1
;     for (int it = 0; it < nmine; ++it) {
;         const int t = vb + it * G;
;         const int xcd = t & 7, j = t >> 3, m0 = (32 * xcd + (j >> 3)) * 128, c0 = (j & 7) * 128;
;         f32x16 mg[2];
; #pragma unroll
;         for (int i = 0; i < 16; ++i) { mg[0][i] = 0.f; mg[1][i] = 0.f; }
; #pragma unroll 1
;         for (int n = 0; n < 4; ++n) {
;             const int g0 = it * 24 + n * 6;
;             f32x16 g[2], y[2];
; #pragma unroll
;             for (int i = 0; i < 16; ++i) { g[0][i] = 0.f; g[1][i] = 0.f; y[0][i] = 0.f; y[1][i] = 0.f; }
;             __syncthreads(); mma21(g, sA, sB, wr, wc, r, h); stg4_commit(R1, sA + TILE_E, sB + TILE_E, srow, skc); ISS(R1, g0 + 3);
;             __syncthreads(); mma21(g, sA + TILE_E, sB + TILE_E, wr, wc, r, h); stg4_commit(R0, sA, sB, srow, skc); ISS(R0, g0 + 4);
; #pragma unroll
;             for (int mi = 0; mi < 2; ++mi)
; #pragma unroll
;                 for (int i = 0; i < 16; ++i) g[mi][i] = __builtin_amdgcn_rcpf(1.f + fexp2(-g[mi][i] * LOG2E));
;             __syncthreads(); mma21(y, sA, sB, wr, wc, r, h); stg4_commit(R1, sA + TILE_E, sB + TILE_E, srow, skc); ISS(R1, g0 + 5);
;             __syncthreads(); mma21(y, sA + TILE_E, sB + TILE_E, wr, wc, r, h); stg4_commit(R0, sA, sB, srow, skc); ISS(R0, g0 + 6);
;             __syncthreads(); mma21(y, sA, sB, wr, wc, r, h); stg4_commit(R1, sA + TILE_E, sB + TILE_E, srow, skc); ISS(R1, g0 + 7);
;             __syncthreads(); mma21(y, sA + TILE_E, sB + TILE_E, wr, wc, r, h); stg4_commit(R0, sA, sB, srow, skc); ISS(R0, g0 + 8);
; #pragma unroll
;             for (int mi = 0; mi < 2; ++mi)
; #pragma unroll
;                 for (int i = 0; i < 16; ++i) mg[mi][i] += g[mi][i] * y[mi][i];
;         }
;         bf16_t* pb = (bf16_t*)(ws + O_XB) + (size_t)(m0 + 64 * wr + 4 * h) * 1024 + c0 + 32 * wc + r;
; #pragma unroll
;         for (int mi = 0; mi < 2; ++mi)
; #pragma unroll
;             for (int qd = 0; qd < 4; ++qd) {
;                 bf16_t* q = opaque(pb + (size_t)(32 * mi + 8 * qd) * 1024);
; #pragma unroll
;                 for (int e = 0; e < 4; ++e) q[e * 1024] = tobf(mg[mi][4 * qd + e]);
;             }
;         __builtin_amdgcn_s_waitcnt(0x0F70);
;     }
	v_exp_f32_e32 v23, v23
	v_exp_f32_e32 v24, v24
	v_exp_f32_e32 v25, v25
	v_add_f32_e32 v18, 1.0, v18
	v_add_f32_e32 v19, 1.0, v19
	v_add_f32_e32 v20, 1.0, v20
	v_add_f32_e32 v21, 1.0, v21
	v_add_f32_e32 v22, 1.0, v22
	v_add_f32_e32 v23, 1.0, v23
	v_add_f32_e32 v24, 1.0, v24
	v_add_f32_e32 v25, 1.0, v25
	v_rcp_f32_e32 v18, v18
	v_rcp_f32_e32 v19, v19
	v_rcp_f32_e32 v20, v20
	v_rcp_f32_e32 v21, v21
	v_rcp_f32_e32 v22, v22
	v_rcp_f32_e32 v23, v23
	v_rcp_f32_e32 v24, v24
	v_rcp_f32_e32 v25, v25
	v_fmac_f32_e32 v82, v18, v50
	v_fmac_f32_e32 v83, v19, v51
	v_fmac_f32_e32 v84, v20, v52
	v_fmac_f32_e32 v85, v21, v53
	v_fmac_f32_e32 v86, v22, v54
	v_fmac_f32_e32 v87, v23, v55
	v_fmac_f32_e32 v88, v24, v56
	v_fmac_f32_e32 v89, v25, v57
	v_mul_f32_e32 v26, 0xbfb8aa3b, v26
	v_mul_f32_e32 v27, 0xbfb8aa3b, v27
	v_mul_f32_e32 v28, 0xbfb8aa3b, v28
	v_mul_f32_e32 v29, 0xbfb8aa3b, v29
	v_mul_f32_e32 v30, 0xbfb8aa3b, v30
	v_mul_f32_e32 v31, 0xbfb8aa3b, v31
	v_mul_f32_e32 v32, 0xbfb8aa3b, v32
	v_mul_f32_e32 v33, 0xbfb8aa3b, v33
	v_exp_f32_e32 v26, v26
	v_exp_f32_e32 v27, v27
	v_exp_f32_e32 v28, v28
	v_exp_f32_e32 v29, v29
	v_exp_f32_e32 v30, v30
	v_exp_f32_e32 v31, v31
	v_exp_f32_e32 v32, v32
	v_exp_f32_e32 v33, v33
	v_add_f32_e32 v26, 1.0, v26
	v_add_f32_e32 v27, 1.0, v27
	v_add_f32_e32 v28, 1.0, v28
	v_add_f32_e32 v29, 1.0, v29
	v_add_f32_e32 v30, 1.0, v30
	v_add_f32_e32 v31, 1.0, v31
	v_add_f32_e32 v32, 1.0, v32
	v_add_f32_e32 v33, 1.0, v33
	v_rcp_f32_e32 v26, v26
	v_rcp_f32_e32 v27, v27
	v_rcp_f32_e32 v28, v28
	v_rcp_f32_e32 v29, v29
	v_rcp_f32_e32 v30, v30
	v_rcp_f32_e32 v31, v31
	v_rcp_f32_e32 v32, v32
	v_rcp_f32_e32 v33, v33
	v_fmac_f32_e32 v90, v26, v58
	v_fmac_f32_e32 v91, v27, v59
	v_fmac_f32_e32 v92, v28, v60
	v_fmac_f32_e32 v93, v29, v61
	v_fmac_f32_e32 v94, v30, v62
	v_fmac_f32_e32 v95, v31, v63
	v_fmac_f32_e32 v96, v32, v64
	v_fmac_f32_e32 v97, v33, v65
	s_cmp_eq_u32 s24, 0
	s_cbranch_scc0 .Lp4_tile_end
	s_mov_b32 s24, 1
	s_branch .Lp4_body
.Lp4_tile_end:
	s_lshl_b32 s20, s26, 11
	s_lshl_b32 s21, s27, 1
	s_add_i32 s20, s20, s21
	s_add_u32 s16, s14, s20
	s_addc_u32 s17, s15, 0
	v_cvt_pk_bf16_f32 v202, v66, v67
	v_cvt_pk_bf16_f32 v203, v68, v69
	s_add_u32 s18, s16, 0x0
	s_addc_u32 s19, s17, 0
	global_store_short v200, v202, s[18:19]
	global_store_short_d16_hi v200, v202, s[18:19] offset:2048
	s_add_u32 s18, s18, 0x1000
	s_addc_u32 s19, s19, 0
	global_store_short v200, v203, s[18:19]
	global_store_short_d16_hi v200, v203, s[18:19] offset:2048
	s_nop 0
	v_cvt_pk_bf16_f32 v202, v70, v71
	v_cvt_pk_bf16_f32 v203, v72, v73
	s_add_u32 s18, s16, 0x4000
	s_addc_u32 s19, s17, 0
	global_store_short v200, v202, s[18:19]
	global_store_short_d16_hi v200, v202, s[18:19] offset:2048
	s_add_u32 s18, s18, 0x1000
	s_addc_u32 s19, s19, 0
	global_store_short v200, v203, s[18:19]
	global_store_short_d16_hi v200, v203, s[18:19] offset:2048
	s_nop 0
	v_cvt_pk_bf16_f32 v202, v74, v75
	v_cvt_pk_bf16_f32 v203, v76, v77
	s_add_u32 s18, s16, 0x8000
	s_addc_u32 s19, s17, 0
	global_store_short v200, v202, s[18:19]
	global_store_short_d16_hi v200, v202, s[18:19] offset:2048
	s_add_u32 s18, s18, 0x1000
	s_addc_u32 s19, s19, 0
	global_store_short v200, v203, s[18:19]
	global_store_short_d16_hi v200, v203, s[18:19] offset:2048
	s_nop 0
	v_cvt_pk_bf16_f32 v202, v78, v79
	v_cvt_pk_bf16_f32 v203, v80, v81
	s_add_u32 s18, s16, 0xc000
	s_addc_u32 s19, s17, 0
	global_store_short v200, v202, s[18:19]
	global_store_short_d16_hi v200, v202, s[18:19] offset:2048
	s_add_u32 s18, s18, 0x1000
	s_addc_u32 s19, s19, 0
	global_store_short v200, v203, s[18:19]
	global_store_short_d16_hi v200, v203, s[18:19] offset:2048
	s_nop 0
	v_cvt_pk_bf16_f32 v202, v82, v83
	v_cvt_pk_bf16_f32 v203, v84, v85
	s_add_u32 s18, s16, 0x10000
	s_addc_u32 s19, s17, 0
	global_store_short v200, v202, s[18:19]
	global_store_short_d16_hi v200, v202, s[18:19] offset:2048
	s_add_u32 s18, s18, 0x1000
	s_addc_u32 s19, s19, 0
	global_store_short v200, v203, s[18:19]
	global_store_short_d16_hi v200, v203, s[18:19] offset:2048
	s_nop 0
	v_cvt_pk_bf16_f32 v202, v86, v87
	v_cvt_pk_bf16_f32 v203, v88, v89
	s_add_u32 s18, s16, 0x14000
	s_addc_u32 s19, s17, 0
	global_store_short v200, v202, s[18:19]
	global_store_short_d16_hi v200, v202, s[18:19] offset:2048
	s_add_u32 s18, s18, 0x1000
	s_addc_u32 s19, s19, 0
	global_store_short v200, v203, s[18:19]
	global_store_short_d16_hi v200, v203, s[18:19] offset:2048
	s_nop 0
	v_cvt_pk_bf16_f32 v202, v90, v91
	v_cvt_pk_bf16_f32 v203, v92, v93
	s_add_u32 s18, s16, 0x18000
	s_addc_u32 s19, s17, 0
	global_store_short v200, v202, s[18:19]
	global_store_short_d16_hi v200, v202, s[18:19] offset:2048
	s_add_u32 s18, s18, 0x1000
	s_addc_u32 s19, s19, 0
	global_store_short v200, v203, s[18:19]
	global_store_short_d16_hi v200, v203, s[18:19] offset:2048
	s_nop 0
	v_cvt_pk_bf16_f32 v202, v94, v95
	v_cvt_pk_bf16_f32 v203, v96, v97
	s_add_u32 s18, s16, 0x1c000
	s_addc_u32 s19, s17, 0
	global_store_short v200, v202, s[18:19]
	global_store_short_d16_hi v200, v202, s[18:19] offset:2048
	s_add_u32 s18, s18, 0x1000
	s_addc_u32 s19, s19, 0
	global_store_short v200, v203, s[18:19]
	global_store_short_d16_hi v200, v203, s[18:19] offset:2048
	s_nop 0
	v_mov_b32_e32 v66, 0
	v_mov_b32_e32 v67, 0
	v_mov_b32_e32 v68, 0
	v_mov_b32_e32 v69, 0
	v_mov_b32_e32 v70, 0
	v_mov_b32_e32 v71, 0
	v_mov_b32_e32 v72, 0
	v_mov_b32_e32 v73, 0
	v_mov_b32_e32 v74, 0
	v_mov_b32_e32 v75, 0
	v_mov_b32_e32 v76, 0
	v_mov_b32_e32 v77, 0
	v_mov_b32_e32 v78, 0
	v_mov_b32_e32 v79, 0
	v_mov_b32_e32 v80, 0
	v_mov_b32_e32 v81, 0
	v_mov_b32_e32 v82, 0
	v_mov_b32_e32 v83, 0
	v_mov_b32_e32 v84, 0
	v_mov_b32_e32 v85, 0
	v_mov_b32_e32 v86, 0
	v_mov_b32_e32 v87, 0
	v_mov_b32_e32 v88, 0
	v_mov_b32_e32 v89, 0
	v_mov_b32_e32 v90, 0
	v_mov_b32_e32 v91, 0
	v_mov_b32_e32 v92, 0
	v_mov_b32_e32 v93, 0
	v_mov_b32_e32 v94, 0
	v_mov_b32_e32 v95, 0
	v_mov_b32_e32 v96, 0
	v_mov_b32_e32 v97, 0
	s_cmp_eq_u32 s30, 0
	s_cbranch_scc1 .Lp4_done
	s_mov_b32 s25, s29
	s_and_b32 s20, s25, 7
	s_lshl_b32 s20, s20, 5
	s_lshr_b32 s21, s25, 6
	s_add_i32 s20, s20, s21
	s_lshl_b32 s26, s20, 7
	s_bfe_u32 s20, s25, 0x30003
	s_lshl_b32 s27, s20, 7
	s_mov_b32 s24, 0
	s_branch .Lp4_body
.Lp4_done:
.LBB0_892:
	s_waitcnt vmcnt(0)
	v_readlane_b32 s0, v253, 16
	v_readlane_b32 s1, v253, 17
	s_waitcnt lgkmcnt(0)
	s_barrier
	s_and_saveexec_b64 s[36:37], s[0:1]
	s_cbranch_execz .LBB0_936
	v_readlane_b32 s38, v253, 18
	v_readlane_b32 s39, v253, 19
	s_getreg_b32 s3, hwreg(HW_REG_XCC_ID, 0, 4)
	s_waitcnt vmcnt(0) expcnt(0) lgkmcnt(0)
	ds_read_b32 v2, v252
	ds_read_b32 v0, v229
	s_and_b32 s3, s3, 15
	s_waitcnt lgkmcnt(1)
	v_cmp_ne_u32_e32 vcc, 0, v2
	s_cbranch_vccnz .LBB0_907
	s_add_u32 s4, s38, 0x1000
	s_addc_u32 s5, s39, 0
	s_add_u32 s6, s38, 0x1100
	s_addc_u32 s7, s39, 0
	s_add_u32 s8, s38, 0x1200
	s_addc_u32 s9, s39, 0
	s_add_u32 s10, s38, 0x1300
	s_addc_u32 s11, s39, 0
	s_mov_b32 s30, 1
	s_mov_b64 s[12:13], 0
	s_branch .LBB0_897
